# sibling-group barrier: the 4 workgroups sharing an M-tile sync on a per-group counter instead of the grid barrier at 9 of 13 phase boundaries per layer (h/hidden/mrg/row-stat dependencies are M-tile-l
# speedup vs baseline: 1.0367x; 1.0120x over previous
.LBB0_2:
	s_or_b64 exec, exec, s[4:5]
	s_load_dwordx16 s[16:31], s[0:1], 0x0
	s_add_u32 s34, s72, 0x267e2000
	s_waitcnt lgkmcnt(0)
	s_barrier
	v_writelane_b32 v253, s16, 11
	s_addc_u32 s35, s73, 0
	s_getreg_b32 s8, hwreg(HW_REG_XCC_ID, 0, 4)
	v_writelane_b32 v253, s17, 12
	v_writelane_b32 v253, s18, 13
	v_writelane_b32 v253, s19, 14
	v_writelane_b32 v253, s20, 15
	v_writelane_b32 v253, s21, 16
	v_writelane_b32 v253, s22, 17
	v_writelane_b32 v253, s23, 18
	v_writelane_b32 v253, s24, 19
	v_writelane_b32 v253, s25, 20
	v_writelane_b32 v253, s26, 21
	v_writelane_b32 v253, s27, 22
	v_writelane_b32 v253, s28, 23
	v_writelane_b32 v253, s29, 24
	v_writelane_b32 v253, s30, 25
	v_writelane_b32 v253, s31, 26
	s_mov_b64 s[4:5], exec
	v_readlane_b32 s6, v253, 9
	v_readlane_b32 s7, v253, 10
	s_and_b64 s[6:7], s[4:5], s[6:7]
	s_mov_b64 exec, s[6:7]
	s_cbranch_execz .LBB0_5
	s_mov_b64 s[6:7], exec
	v_mbcnt_lo_u32_b32 v1, s6, 0
	v_mbcnt_hi_u32_b32 v1, s7, v1
	v_cmp_eq_u32_e32 vcc, 0, v1
	s_and_b64 s[10:11], exec, vcc
	s_mov_b64 exec, s[10:11]
	s_cbranch_execz .LBB0_5
	s_lshl_b32 s8, s8, 8
	s_and_b32 s8, s8, 0xf00
	s_bcnt1_i32_b64 s6, s[6:7]
	v_mov_b32_e32 v1, s8
	v_mov_b32_e32 v2, s6
	global_atomic_add v1, v2, s[34:35] offset:1024
	v_readlane_b32 s9, v253, 0
	s_and_b32 s9, s9, 63
	s_lshl_b32 s9, s9, 2
	s_lshr_b32 s10, s8, 8
	s_lshl_b32 s10, 1, s10
	v_mov_b32_e32 v3, s9
	v_mov_b32_e32 v4, s10
	global_atomic_or v3, v4, s[34:35] offset:256

.LBB0_71:
	s_and_b32 s2, s33, 15
	s_cmp_eq_u32 s2, 0
	s_cselect_b64 vcc, -1, 0
	s_cmp_eq_u32 s2, 1
	v_cndmask_b32_e32 v16, 0, v15, vcc
	s_cselect_b64 vcc, -1, 0
	s_cmp_eq_u32 s2, 2
	v_cndmask_b32_e32 v16, v16, v0, vcc
	s_cselect_b64 vcc, -1, 0
	s_cmp_eq_u32 s2, 3
	v_cndmask_b32_e32 v16, v16, v1, vcc
	s_cselect_b64 vcc, -1, 0
	s_cmp_eq_u32 s2, 4
	v_cndmask_b32_e32 v16, v16, v2, vcc
	s_cselect_b64 vcc, -1, 0
	s_cmp_eq_u32 s2, 5
	v_cndmask_b32_e32 v16, v16, v3, vcc
	s_cselect_b64 vcc, -1, 0
	s_cmp_eq_u32 s2, 6
	v_cndmask_b32_e32 v16, v16, v4, vcc
	s_cselect_b64 vcc, -1, 0
	s_cmp_eq_u32 s2, 7
	v_cndmask_b32_e32 v16, v16, v5, vcc
	s_cselect_b64 vcc, -1, 0
	s_cmp_eq_u32 s2, 8
	v_cndmask_b32_e32 v16, v16, v6, vcc
	s_cselect_b64 vcc, -1, 0
	s_cmp_eq_u32 s2, 9
	v_cndmask_b32_e32 v16, v16, v7, vcc
	s_cselect_b64 vcc, -1, 0
	s_cmp_eq_u32 s2, 10
	v_cndmask_b32_e32 v16, v16, v8, vcc
	s_cselect_b64 vcc, -1, 0
	s_cmp_eq_u32 s2, 11
	v_cndmask_b32_e32 v16, v16, v9, vcc
	s_cselect_b64 vcc, -1, 0
	s_cmp_eq_u32 s2, 12
	v_cndmask_b32_e32 v16, v16, v10, vcc
	s_cselect_b64 vcc, -1, 0
	s_cmp_eq_u32 s2, 13
	v_cndmask_b32_e32 v16, v16, v11, vcc
	s_cselect_b64 vcc, -1, 0
	s_cmp_eq_u32 s2, 14
	v_cndmask_b32_e32 v16, v16, v12, vcc
	s_cselect_b64 vcc, -1, 0
	s_cmp_eq_u32 s2, 15
	v_cndmask_b32_e32 v16, v16, v13, vcc
	s_cselect_b64 vcc, -1, 0
	v_cndmask_b32_e32 v16, v16, v14, vcc
	v_cmp_ne_u32_e32 vcc, 0, v15
	s_nop 1
	v_cndmask_b32_e64 v15, 0, 1, vcc
	v_cmp_ne_u32_e32 vcc, 0, v0
	s_nop 1
	v_addc_co_u32_e32 v0, vcc, 0, v15, vcc
	v_cmp_ne_u32_e32 vcc, 0, v1
	s_nop 1
	v_cndmask_b32_e64 v1, 0, 1, vcc
	v_cmp_ne_u32_e32 vcc, 0, v2
	v_mov_b32_e32 v2, 0x24000
	s_nop 0
	v_addc_co_u32_e32 v0, vcc, v0, v1, vcc
	v_cmp_ne_u32_e32 vcc, 0, v3
	s_nop 1
	v_cndmask_b32_e64 v1, 0, 1, vcc
	v_cmp_ne_u32_e32 vcc, 0, v4
	s_nop 1
	v_addc_co_u32_e32 v0, vcc, v0, v1, vcc
	v_cmp_ne_u32_e32 vcc, 0, v5
	s_nop 1
	v_cndmask_b32_e64 v1, 0, 1, vcc
	v_cmp_ne_u32_e32 vcc, 0, v6
	s_nop 1
	v_addc_co_u32_e32 v0, vcc, v0, v1, vcc
	v_cmp_ne_u32_e32 vcc, 0, v7
	s_nop 1
	v_cndmask_b32_e64 v1, 0, 1, vcc
	v_cmp_ne_u32_e32 vcc, 0, v8
	s_nop 1
	v_addc_co_u32_e32 v0, vcc, v0, v1, vcc
	v_cmp_ne_u32_e32 vcc, 0, v9
	s_nop 1
	v_cndmask_b32_e64 v1, 0, 1, vcc
	v_cmp_ne_u32_e32 vcc, 0, v10
	s_nop 1
	v_addc_co_u32_e32 v0, vcc, v0, v1, vcc
	v_cmp_ne_u32_e32 vcc, 0, v11
	s_nop 1
	v_cndmask_b32_e64 v1, 0, 1, vcc
	v_cmp_ne_u32_e32 vcc, 0, v12
	s_nop 1
	v_addc_co_u32_e32 v0, vcc, v0, v1, vcc
	v_cmp_ne_u32_e32 vcc, 0, v13
	s_nop 1
	v_cndmask_b32_e64 v1, 0, 1, vcc
	v_cmp_ne_u32_e32 vcc, 0, v14
	s_nop 1
	v_addc_co_u32_e32 v0, vcc, v0, v1, vcc
	v_max_u32_e32 v1, 1, v16
	v_max_u32_e32 v0, 1, v0
	ds_write_b32 v2, v1
	v_mov_b32_e32 v1, 0x24004
	ds_write_b32 v1, v0
	v_readlane_b32 s8, v253, 0
	s_and_b32 s8, s8, 63
	s_lshl_b32 s8, s8, 2
	s_add_u32 s10, s72, 0x267e2000
	s_addc_u32 s11, s73, 0
	v_mov_b32_e32 v3, s8
	global_load_dword v4, v3, s[10:11] offset:256 sc1
	s_waitcnt vmcnt(0)
	v_bcnt_u32_b32 v4, v4, 0
	v_cmp_ne_u32_e32 vcc, 1, v4
	v_mov_b32_e32 v3, 0x24008
	s_nop 0
	v_cndmask_b32_e64 v4, 0, 1, vcc
	ds_write_b32 v3, v4
	s_waitcnt lgkmcnt(0)

.LBB0_78:
	s_or_b64 exec, exec, s[4:5]
	s_getreg_b32 s8, hwreg(HW_REG_XCC_ID, 0, 4)
	s_waitcnt vmcnt(0)
	s_barrier
	s_mov_b64 s[4:5], exec
	v_readlane_b32 s6, v253, 9
	v_readlane_b32 s7, v253, 10
	s_and_b64 s[6:7], s[4:5], s[6:7]
	s_mov_b64 exec, s[6:7]
	s_cbranch_execz .LBB0_108
	v_readlane_b32 s9, v254, 57
	s_cmp_eq_u32 s9, 0
	s_cbranch_scc1 .Llb_grid_b1
	v_readlane_b32 s8, v253, 43
	v_readlane_b32 s9, v253, 44
	v_readlane_b32 s10, v253, 0
	ds_read_b32 v5, v156 offset:8
	s_and_b32 s10, s10, 63
	s_lshl_b32 s10, s10, 2
	v_mov_b32_e32 v0, s10
	v_mov_b32_e32 v1, 1
	s_waitcnt vmcnt(0) lgkmcnt(0)
	v_readfirstlane_b32 s11, v5
	s_cmp_eq_u32 s11, 0
	s_cbranch_scc1 .Llb_rel_b1
	buffer_wbl2 sc1
	s_waitcnt vmcnt(0)
.Llb_rel_b1:
	global_atomic_add v2, v0, v1, s[8:9] sc0
	s_mov_b32 s11, 0
	s_waitcnt vmcnt(0)
	v_readfirstlane_b32 s12, v2
	s_or_b32 s12, s12, 3
	s_add_u32 s12, s12, 1
.Llb_spin_b1:
	global_load_dword v3, v0, s[8:9] sc1
	s_waitcnt vmcnt(0)
	v_readfirstlane_b32 s13, v3
	s_sub_u32 s13, s13, s12
	s_cmp_ge_i32 s13, 0
	s_cbranch_scc1 .Llb_done_b1
	s_sleep 1
	s_add_u32 s11, s11, 1
	s_cmp_lt_u32 s11, 0x10000
	s_cbranch_scc1 .Llb_spin_b1
.Llb_done_b1:
	buffer_inv sc1
	s_waitcnt vmcnt(0)
	s_branch .LBB0_108
.Llb_grid_b1:
	v_readlane_b32 s6, v253, 43
	s_lshl_b32 s8, s8, 8
	v_readlane_b32 s7, v253, 44
	s_and_b32 s8, s8, 0xf00
	s_add_u32 s13, s6, s8
	s_addc_u32 s12, s7, 0
	v_mov_b32_e32 v0, s13
	v_add_co_u32_e32 v2, vcc, 0x1000, v0
	v_mov_b32_e32 v0, s12
	s_nop 0
	v_addc_co_u32_e32 v3, vcc, 0, v0, vcc
	s_waitcnt vmcnt(0) expcnt(0) lgkmcnt(0)
	ds_read_b32 v4, v156
	ds_read_b32 v1, v157
	flat_atomic_add v2, v[2:3], v158 offset:1024 sc0
	s_waitcnt lgkmcnt(0)
	v_cvt_f32_u32_e32 v0, v4
	v_sub_u32_e32 v3, 0, v4
	v_rcp_iflag_f32_e32 v0, v0
	s_nop 0
	v_mul_f32_e32 v0, 0x4f7ffffe, v0
	v_cvt_u32_f32_e32 v0, v0
	v_mul_lo_u32 v3, v3, v0
	v_mul_hi_u32 v3, v0, v3
	v_add_u32_e32 v0, v0, v3
	s_waitcnt vmcnt(0)
	v_mul_hi_u32 v0, v2, v0
	v_mul_lo_u32 v3, v0, v4
	v_sub_u32_e32 v3, v2, v3
	v_add_u32_e32 v5, 1, v0
	v_cmp_ge_u32_e32 vcc, v3, v4
	v_add_u32_e32 v2, 1, v2
	s_nop 0
	v_cndmask_b32_e32 v0, v0, v5, vcc
	v_sub_u32_e32 v5, v3, v4
	v_cndmask_b32_e32 v3, v3, v5, vcc
	v_add_u32_e32 v5, 1, v0
	v_cmp_ge_u32_e32 vcc, v3, v4
	s_nop 1
	v_cndmask_b32_e32 v0, v0, v5, vcc
	v_mul_lo_u32 v3, v4, v0
	v_add_u32_e32 v3, v3, v4
	v_cmp_ne_u32_e32 vcc, v2, v3
	s_and_saveexec_b64 s[8:9], vcc
	s_xor_b64 s[8:9], exec, s[8:9]
	s_cbranch_execz .LBB0_92
	v_mov_b32_e32 v1, s13
	v_add_co_u32_e32 v2, vcc, 0x2000, v1
	v_mov_b32_e32 v1, s12
	s_nop 0
	v_addc_co_u32_e32 v3, vcc, 0, v1, vcc
	flat_load_dword v1, v[2:3] offset:1024 sc1
	s_add_u32 s14, s13, 0x2400
	s_addc_u32 s15, s12, 0
	s_waitcnt vmcnt(0) lgkmcnt(0)
	v_cmp_eq_u32_e32 vcc, v1, v0
	s_and_saveexec_b64 s[10:11], vcc
	s_cbranch_execz .LBB0_91
	s_mov_b32 s21, 1
	s_mov_b64 s[26:27], 0
	s_branch .LBB0_83

.Lconv_ret1:
	s_getreg_b32 s8, hwreg(HW_REG_XCC_ID, 0, 4)
	s_waitcnt vmcnt(0)
	s_waitcnt vmcnt(0)
	s_barrier
	s_mov_b64 s[4:5], exec
	v_readlane_b32 s6, v253, 9
	v_readlane_b32 s7, v253, 10
	s_and_b64 s[6:7], s[4:5], s[6:7]
	s_mov_b64 exec, s[6:7]
	s_cbranch_execz .LBB0_147
	v_readlane_b32 s8, v253, 43
	v_readlane_b32 s9, v253, 44
	v_readlane_b32 s10, v253, 0
	ds_read_b32 v5, v156 offset:8
	s_and_b32 s10, s10, 63
	s_lshl_b32 s10, s10, 2
	v_mov_b32_e32 v0, s10
	v_mov_b32_e32 v1, 1
	s_waitcnt vmcnt(0) lgkmcnt(0)
	v_readfirstlane_b32 s11, v5
	s_cmp_eq_u32 s11, 0
	s_cbranch_scc1 .Llb_rel_b2
	buffer_wbl2 sc1
	s_waitcnt vmcnt(0)

.LBB0_156:
	s_getreg_b32 s6, hwreg(HW_REG_XCC_ID, 0, 4)
	s_waitcnt vmcnt(0)
	s_barrier
	s_mov_b64 s[0:1], exec
	v_readlane_b32 s4, v253, 9
	v_readlane_b32 s5, v253, 10
	s_and_b64 s[4:5], s[0:1], s[4:5]
	s_mov_b64 exec, s[4:5]
	s_cbranch_execz .LBB0_186
	v_readlane_b32 s8, v253, 43
	v_readlane_b32 s9, v253, 44
	v_readlane_b32 s10, v253, 0
	ds_read_b32 v5, v156 offset:8
	s_and_b32 s10, s10, 63
	s_lshl_b32 s10, s10, 2
	v_mov_b32_e32 v0, s10
	v_mov_b32_e32 v1, 1
	s_waitcnt vmcnt(0) lgkmcnt(0)
	v_readfirstlane_b32 s11, v5
	s_cmp_eq_u32 s11, 0
	s_cbranch_scc1 .Llb_rel_b3
	buffer_wbl2 sc1
	s_waitcnt vmcnt(0)

.LBB0_189:
	s_or_b64 exec, exec, s[0:1]
	s_getreg_b32 s6, hwreg(HW_REG_XCC_ID, 0, 4)
	s_waitcnt vmcnt(0)
	s_barrier
	s_mov_b64 s[0:1], exec
	v_readlane_b32 s4, v253, 9
	v_readlane_b32 s5, v253, 10
	s_and_b64 s[4:5], s[0:1], s[4:5]
	s_mov_b64 exec, s[4:5]
	s_cbranch_execz .LBB0_219
	v_readlane_b32 s8, v253, 43
	v_readlane_b32 s9, v253, 44
	v_readlane_b32 s10, v253, 0
	ds_read_b32 v5, v156 offset:8
	s_and_b32 s10, s10, 63
	s_lshl_b32 s10, s10, 2
	v_mov_b32_e32 v0, s10
	v_mov_b32_e32 v1, 1
	s_waitcnt vmcnt(0) lgkmcnt(0)
	v_readfirstlane_b32 s11, v5
	s_cmp_eq_u32 s11, 0
	s_cbranch_scc1 .Llb_rel_b4
	buffer_wbl2 sc1
	s_waitcnt vmcnt(0)

.Lconv_ret3:
	s_getreg_b32 s6, hwreg(HW_REG_XCC_ID, 0, 4)
	s_waitcnt vmcnt(0)
	s_waitcnt vmcnt(0)
	s_barrier
	s_mov_b64 s[0:1], exec
	v_readlane_b32 s4, v253, 9
	v_readlane_b32 s5, v253, 10
	s_and_b64 s[4:5], s[0:1], s[4:5]
	s_mov_b64 exec, s[4:5]
	s_cbranch_execz .LBB0_696
	v_readlane_b32 s8, v253, 43
	v_readlane_b32 s9, v253, 44
	v_readlane_b32 s10, v253, 0
	ds_read_b32 v5, v156 offset:8
	s_and_b32 s10, s10, 63
	s_lshl_b32 s10, s10, 2
	v_mov_b32_e32 v0, s10
	v_mov_b32_e32 v1, 1
	s_waitcnt vmcnt(0) lgkmcnt(0)
	v_readfirstlane_b32 s11, v5
	s_cmp_eq_u32 s11, 0
	s_cbranch_scc1 .Llb_rel_b12
	buffer_wbl2 sc1
	s_waitcnt vmcnt(0)

.Llb_to74:
	s_getpc_b64 s[98:99]

.LBB0_706:
	v_readlane_b32 s8, v253, 43
	v_readlane_b32 s9, v253, 44
	v_readlane_b32 s10, v253, 0
	ds_read_b32 v5, v156 offset:8
	s_and_b32 s10, s10, 63
	s_lshl_b32 s10, s10, 2
	v_mov_b32_e32 v0, s10
	v_mov_b32_e32 v1, 1
	s_waitcnt vmcnt(0) lgkmcnt(0)
	v_readfirstlane_b32 s11, v5
	s_cmp_eq_u32 s11, 0
	s_cbranch_scc1 .Llb_rel_b13
	buffer_wbl2 sc1
	s_waitcnt vmcnt(0)

.Llb_done_b13:
	buffer_inv sc1
	s_waitcnt vmcnt(0)
	s_branch .Llb_to74
	v_readlane_b32 s4, v253, 43
	s_lshl_b32 s6, s6, 8
	v_readlane_b32 s5, v253, 44
	s_and_b32 s6, s6, 0xf00
	s_add_u32 s13, s4, s6
	s_addc_u32 s12, s5, 0
	v_mov_b32_e32 v0, s13
	v_add_co_u32_e32 v2, vcc, 0x1000, v0
	v_mov_b32_e32 v0, s12
	s_nop 0
	v_addc_co_u32_e32 v3, vcc, 0, v0, vcc
	s_waitcnt vmcnt(0) expcnt(0) lgkmcnt(0)
	ds_read_b32 v4, v156
	ds_read_b32 v1, v157
	flat_atomic_add v2, v[2:3], v158 offset:1024 sc0
	s_waitcnt lgkmcnt(0)
	v_cvt_f32_u32_e32 v0, v4
	v_sub_u32_e32 v3, 0, v4
	v_rcp_iflag_f32_e32 v0, v0
	s_nop 0
	v_mul_f32_e32 v0, 0x4f7ffffe, v0
	v_cvt_u32_f32_e32 v0, v0
	v_mul_lo_u32 v3, v3, v0
	v_mul_hi_u32 v3, v0, v3
	v_add_u32_e32 v0, v0, v3
	s_waitcnt vmcnt(0)
	v_mul_hi_u32 v0, v2, v0
	v_mul_lo_u32 v3, v0, v4
	v_sub_u32_e32 v3, v2, v3
	v_add_u32_e32 v5, 1, v0
	v_cmp_ge_u32_e32 vcc, v3, v4
	v_add_u32_e32 v2, 1, v2
	s_nop 0
	v_cndmask_b32_e32 v0, v0, v5, vcc
	v_sub_u32_e32 v5, v3, v4
	v_cndmask_b32_e32 v3, v3, v5, vcc
	v_add_u32_e32 v5, 1, v0
	v_cmp_ge_u32_e32 vcc, v3, v4
	s_nop 1
	v_cndmask_b32_e32 v0, v0, v5, vcc
	v_mul_lo_u32 v3, v4, v0
	v_add_u32_e32 v3, v3, v4
	v_cmp_ne_u32_e32 vcc, v2, v3
	s_and_saveexec_b64 s[6:7], vcc
	s_xor_b64 s[6:7], exec, s[6:7]
	s_cbranch_execz .LBB0_719
	v_mov_b32_e32 v1, s13
	v_add_co_u32_e32 v2, vcc, 0x2000, v1
	v_mov_b32_e32 v1, s12
	s_nop 0
	v_addc_co_u32_e32 v3, vcc, 0, v1, vcc
	flat_load_dword v1, v[2:3] offset:1024 sc1
	s_add_u32 s10, s13, 0x2400
	s_addc_u32 s11, s12, 0
	s_waitcnt vmcnt(0) lgkmcnt(0)
	v_cmp_eq_u32_e32 vcc, v1, v0
	s_and_saveexec_b64 s[8:9], vcc
	s_cbranch_execz .LBB0_718
	s_mov_b32 s21, 1
	s_mov_b64 s[14:15], 0
	s_branch .LBB0_710
